# SSD phase: odd workgroups run their (bandwidth-bound) sample units before their (latency-bound) prompt unit; on top of v9
# speedup vs baseline: 1.0103x; 1.0050x over previous
.LBB0_333:
	s_or_b64 exec, exec, s[0:1]
	v_readlane_b32 s0, v242, 9
	s_bitcmp0_b32 s0, 2
	s_cselect_b64 s[0:1], -1, 0
	s_xor_b64 s[2:3], s[18:19], -1
	s_or_b64 s[0:1], s[0:1], s[2:3]
	s_mov_b32 s95, 0
	s_and_b64 vcc, exec, s[0:1]
	s_waitcnt lgkmcnt(0)
	s_barrier
	s_mov_b32 s98, 0
	s_bitcmp1_b32 s94, 0
	s_cbranch_scc0 .Lswap_even
	s_mov_b32 s98, 1
	s_branch .LBB0_379
.Lswap_even:
	s_cbranch_vccnz .LBB0_379
.Lswap_prompt:
	v_writelane_b32 v242, s86, 15
	s_add_u32 s38, s80, 0x41a00000
	s_addc_u32 s39, s81, 0
	v_writelane_b32 v242, s87, 16
	v_writelane_b32 v242, s82, 17
	v_writelane_b32 v242, s76, 18
	s_add_u32 s0, s80, 0x600000
	v_lshlrev_b32_e32 v1, 9, v0
	v_writelane_b32 v242, s77, 19
	v_writelane_b32 v242, s78, 20
	v_writelane_b32 v242, s79, 21
	v_writelane_b32 v242, s0, 22
	s_addc_u32 s0, s81, 0
	v_writelane_b32 v242, s0, 23
	v_lshlrev_b32_e32 v2, 4, v0
	s_mov_b32 s0, 0x3e0f0
	v_and_b32_e32 v4, 0xf0, v2
	v_bitop3_b32 v82, v1, s0, v2 bitop3:0xc8
	v_and_b32_e32 v2, 3, v0
	s_lshl_b32 s0, s84, 4
	v_lshrrev_b32_e32 v1, 2, v0
	v_lshlrev_b32_e32 v7, 4, v2
	s_add_u32 s96, s80, 0x43a00000
	s_addc_u32 s97, s81, 0
	v_mov_b32_e32 v87, 0
	v_lshl_or_b32 v86, v1, 13, v7
	v_lshl_add_u64 v[88:89], s[96:97], 0, v[86:87]
	v_lshlrev_b32_e32 v86, 2, v0
	s_movk_i32 s1, 0x80
	v_lshl_add_u64 v[2:3], s[80:81], 0, v[86:87]
	s_mov_b64 s[2:3], 0x800000
	v_cmp_gt_u32_e64 s[76:77], s1, v0
	v_lshl_add_u64 v[90:91], v[2:3], 0, s[2:3]
	v_mul_u32_u24_e32 v1, 40, v1
	s_add_i32 s1, 0, 0x18600
	v_and_b32_e32 v3, 0x1fc, v0
	v_and_b32_e32 v6, 15, v0
	s_add_i32 s23, 0, 0x11000
	v_lshlrev_b32_e32 v1, 1, v1
	v_add_u32_e32 v85, s1, v86
	v_add_u32_e32 v124, s1, v3
	s_add_i32 s1, 0, 0x13800
	v_add3_u32 v5, s23, v1, v7
	v_add3_u32 v125, s1, v1, v7
	v_or_b32_e32 v1, s0, v6
	s_movk_i32 s2, 0x110
	v_lshrrev_b32_e32 v9, 2, v174
	v_mul_lo_u32 v3, v1, s2
	v_and_b32_e32 v84, 12, v9
	v_add_u32_e32 v7, 0, v3
	v_bfe_u32 v3, v0, 2, 2
	v_lshrrev_b32_e32 v10, 1, v0
	v_add_u32_e32 v2, 0, v4
	v_or_b32_e32 v4, v84, v3
	v_and_or_b32 v3, v10, 24, v3
	v_lshrrev_b32_e32 v10, 4, v0
	v_mul_u32_u24_e32 v10, 0x88, v10
	v_lshl_add_u32 v129, v10, 1, v2
	v_or_b32_e32 v10, 0x200, v0
	v_lshrrev_b32_e32 v10, 4, v10
	v_mul_u32_u24_e32 v10, 0x88, v10
	v_lshl_add_u32 v130, v10, 1, v2
	v_or_b32_e32 v10, 0x600, v0
	v_lshrrev_b32_e32 v10, 4, v10
	v_mul_u32_u24_e32 v10, 0x88, v10
	v_lshl_add_u32 v131, v10, 1, v2
	v_or_b32_e32 v10, 2, v84
	v_cmp_gt_u32_e64 s[12:13], v10, v1
	v_or_b32_e32 v10, 16, v84
	s_add_i32 s22, 0, 0x18400
	s_add_i32 s24, 0, 0x18200
	v_and_b32_e32 v126, 48, v0
	s_add_i32 s3, 0, 0x16000
	s_lshl_b32 s6, s84, 5
	v_lshlrev_b32_e32 v16, 2, v10
	v_cmp_gt_u32_e64 s[14:15], v10, v1
	v_cmp_lt_u32_e64 s[16:17], v10, v1
	v_or_b32_e32 v10, 19, v9
	v_add_u32_e32 v128, s3, v126
	s_add_i32 s3, s3, s6
	v_add_u32_e32 v136, s22, v16
	v_add_u32_e32 v137, s24, v16
	v_or_b32_e32 v16, 18, v84
	v_cmp_gt_u32_e64 s[18:19], v10, v1
	v_or_b32_e32 v10, 32, v84
	v_and_b32_e32 v13, 12, v86
	s_cmp_gt_u32 s85, 63
	v_cmp_gt_u32_e64 s[20:21], v16, v1
	v_mul_u32_u24_e32 v4, 40, v4
	v_lshlrev_b32_e32 v16, 2, v10
	v_cmp_gt_u32_e64 s[30:31], v10, v1
	v_cmp_lt_u32_e64 s[34:35], v10, v1
	v_or_b32_e32 v10, 35, v9
	s_mov_b32 s27, s85
	s_mov_b32 s36, s84
	s_cselect_b64 s[84:85], -1, 0
	v_mad_u32_u24 v133, v6, s2, 0
	v_add_lshl_u32 v4, v4, v13, 1
	s_add_i32 s2, 0, 0x11500
	v_add_u32_e32 v142, s22, v16
	v_add_u32_e32 v143, s24, v16
	v_or_b32_e32 v16, 34, v84
	v_cmp_gt_u32_e64 s[42:43], v10, v1
	v_or_b32_e32 v10, 48, v84
	v_add_u32_e32 v139, s2, v4
	s_add_i32 s2, 0, 0x11020
	v_cmp_gt_u32_e64 s[54:55], v16, v1
	v_lshlrev_b32_e32 v16, 2, v10
	v_lshlrev_b32_e32 v8, 1, v6
	v_add_u32_e32 v140, s2, v4
	s_add_i32 s2, 0, 0x11520
	v_add_u32_e32 v144, s22, v16
	v_add_u32_e32 v145, s24, v16
	v_or_b32_e32 v16, 50, v84
	v_add_u32_e32 v15, s3, v8
	v_add_u32_e32 v141, s2, v4
	s_cmpk_gt_u32 s27, 0x7f
	v_cmp_gt_u32_e64 s[2:3], v16, v1
	s_cselect_b64 s[86:87], -1, 0
	s_cmp_lg_u32 s36, 2
	v_writelane_b32 v242, s2, 13
	s_cselect_b64 s[40:41], -1, 0
	v_cmp_gt_u32_e64 s[72:73], v10, v1
	v_writelane_b32 v242, s3, 14
	s_add_i32 s2, 0, 0x11a00
	v_add_u32_e32 v146, s2, v4
	s_add_i32 s2, 0, 0x11f00
	v_add_u32_e32 v147, s2, v4
	s_add_i32 s2, 0, 0x11a20
	v_add_u32_e32 v148, s2, v4
	s_add_i32 s2, 0, 0x11f20
	s_cmpk_gt_u32 s27, 0xff
	v_add_u32_e32 v149, s2, v4
	s_cselect_b64 s[2:3], -1, 0
	s_cmp_lg_u32 s36, 4
	v_cmp_lt_u32_e64 s[56:57], v10, v1
	v_or_b32_e32 v10, 51, v9
	s_cselect_b64 s[52:53], -1, 0
	v_cmp_gt_u32_e64 s[58:59], v10, v1
	v_writelane_b32 v242, s52, 24
	v_or_b32_e32 v10, 64, v84
	v_lshlrev_b32_e32 v16, 2, v10
	v_writelane_b32 v242, s53, 25
	v_cmp_gt_u32_e64 s[52:53], v10, v1
	v_add_u32_e32 v150, s22, v16
	v_add_u32_e32 v151, s24, v16
	v_writelane_b32 v242, s52, 26
	v_or_b32_e32 v16, 0x42, v84
	s_add_i32 s26, 0, 0x12400
	v_writelane_b32 v242, s53, 27
	v_cmp_lt_u32_e64 s[52:53], v10, v1
	v_or_b32_e32 v10, 0x43, v9
	v_add_u32_e32 v154, s26, v4
	v_writelane_b32 v242, s52, 28
	s_add_i32 s26, 0, 0x12900
	v_add_u32_e32 v155, s26, v4
	v_writelane_b32 v242, s53, 29
	v_cmp_gt_u32_e64 s[52:53], v10, v1
	v_or_b32_e32 v10, 0x50, v84
	s_add_i32 s26, 0, 0x12420
	v_writelane_b32 v242, s52, 30
	v_add_u32_e32 v156, s26, v4
	s_add_i32 s26, 0, 0x12920
	v_writelane_b32 v242, s53, 31
	v_cmp_gt_u32_e64 s[52:53], v16, v1
	v_lshlrev_b32_e32 v16, 2, v10
	v_add_u32_e32 v152, s22, v16
	v_writelane_b32 v242, s52, 32
	v_add_u32_e32 v153, s24, v16
	v_or_b32_e32 v16, 0x52, v84
	v_writelane_b32 v242, s53, 33
	v_cmp_gt_u32_e64 s[52:53], v10, v1
	s_cmpk_gt_u32 s27, 0x17f
	s_cselect_b64 s[82:83], -1, 0
	v_writelane_b32 v242, s52, 34
	s_cmp_lg_u32 s36, 6
	v_add_u32_e32 v157, s26, v4
	v_writelane_b32 v242, s53, 35
	v_cmp_lt_u32_e64 s[52:53], v10, v1
	v_or_b32_e32 v10, 0x53, v9
	v_lshlrev_b32_e32 v2, 2, v84
	v_writelane_b32 v242, s52, 36
	v_or_b32_e32 v11, s0, v84
	v_add_u32_e32 v123, s24, v86
	v_writelane_b32 v242, s53, 37
	v_cmp_gt_u32_e64 s[52:53], v10, v1
	v_or_b32_e32 v10, 0x60, v84
	v_add_u32_e32 v134, s22, v2
	v_writelane_b32 v242, s52, 38
	v_add_u32_e32 v135, s24, v2
	v_or_b32_e32 v2, 3, v9
	v_writelane_b32 v242, s53, 39
	v_cmp_gt_u32_e64 s[52:53], v16, v1
	v_lshlrev_b32_e32 v16, 2, v10
	v_add_u32_e32 v158, s22, v16
	v_writelane_b32 v242, s52, 40
	v_add_u32_e32 v159, s24, v16
	v_or_b32_e32 v16, 0x62, v84
	v_writelane_b32 v242, s53, 41
	v_writelane_b32 v242, s27, 42
	s_cselect_b64 s[26:27], -1, 0
	v_writelane_b32 v242, s26, 43
	v_cmp_gt_u32_e64 s[62:63], v16, v1
	s_movk_i32 s25, 0x50
	v_writelane_b32 v242, s27, 44
	v_cmp_gt_u32_e64 s[26:27], v10, v1
	v_lshl_add_u32 v127, v1, 2, s22
	v_cmp_gt_u32_e64 s[6:7], v84, v1
	v_writelane_b32 v242, s26, 45
	v_cmp_lt_u32_e64 s[8:9], v84, v1
	v_cmp_gt_u32_e64 s[10:11], v2, v1
	v_writelane_b32 v242, s27, 46
	v_cmp_lt_u32_e64 s[26:27], v10, v1
	v_or_b32_e32 v10, 0x63, v9
	v_or_b32_e32 v9, 0x73, v9
	v_writelane_b32 v242, s26, 47
	v_cmp_gt_u32_e64 s[68:69], v9, v1
	v_or_b32_e32 v14, s0, v13
	v_writelane_b32 v242, s27, 48
	v_cmp_gt_u32_e64 s[26:27], v10, v1
	v_or_b32_e32 v10, 0x70, v84
	v_lshlrev_b32_e32 v16, 2, v10
	v_add_u32_e32 v161, s24, v16
	v_cmp_gt_u32_e64 s[64:65], v10, v1
	v_cmp_lt_u32_e64 s[66:67], v10, v1
	v_or_b32_e32 v10, 0x72, v84
	s_add_i32 s24, 0, 0x12e00
	v_cmp_gt_u32_e64 s[70:71], v10, v1
	v_add_u32_e32 v162, s24, v4
	s_add_i32 s24, 0, 0x13300
	v_mul_lo_u32 v1, v11, s25
	v_add_u32_e32 v163, s24, v4
	s_add_i32 s24, 0, 0x12e20
	v_add3_u32 v167, s23, v1, v8
	v_mul_u32_u24_e32 v1, 0x88, v3
	v_add_u32_e32 v164, s24, v4
	s_add_i32 s24, 0, 0x13320
	v_or_b32_e32 v172, 3, v11
	v_add_lshl_u32 v1, v14, v1, 1
	v_mul_u32_u24_e32 v3, 40, v3
	v_add_u32_e32 v122, s22, v86
	v_add_u32_e32 v138, s23, v4
	v_writelane_b32 v242, s26, 49
	v_add_u32_e32 v160, s22, v16
	v_add_u32_e32 v165, s24, v4
	v_lshl_add_u32 v166, v11, 2, s22
	v_lshl_add_u32 v173, v172, 2, s22
	s_add_i32 s22, 0, 0x440
	v_add_lshl_u32 v3, v3, v13, 1
	v_add_u32_e32 v4, 0x2200, v1
	v_writelane_b32 v242, s27, 50
	s_add_i32 s23, 0, 0x13940
	s_add_i32 s24, 0, 0x13820
	s_add_i32 s25, 0, 0x13960
	v_add_u32_e32 v182, 0, v4
	v_add_u32_e32 v183, s22, v4
	v_add_u32_e32 v4, 0xa00, v3
	v_writelane_b32 v242, s38, 51
	v_add_u32_e32 v176, 0, v1
	v_add_u32_e32 v177, s22, v1
	v_add_u32_e32 v184, s1, v4
	v_add_u32_e32 v185, s23, v4
	v_add_u32_e32 v186, s24, v4
	v_add_u32_e32 v187, s25, v4
	v_add_u32_e32 v4, 0x4400, v1
	v_add_u32_e32 v1, 0x6600, v1
	v_lshl_add_u32 v13, v0, 1, 0
	v_writelane_b32 v242, s39, 52
	v_add_u32_e32 v188, 0, v4
	v_add_u32_e32 v189, s22, v4
	v_add_u32_e32 v4, 0x1400, v3
	v_add_u32_e32 v194, 0, v1
	v_add_u32_e32 v195, s22, v1
	v_add_u32_e32 v1, 0x1e00, v3
	v_add_u32_e32 v201, 0x16c00, v13
	s_mov_b32 s22, s36
	v_lshlrev_b32_e32 v13, 10, v174
	v_add_u32_e32 v178, s1, v3
	v_add_u32_e32 v179, s23, v3
	v_add_u32_e32 v190, s1, v4
	v_add_u32_e32 v191, s23, v4
	v_add_u32_e32 v196, s1, v1
	v_add_u32_e32 v197, s23, v1
	v_add_u32_e32 v198, s24, v1
	v_add_u32_e32 v199, s25, v1
	v_sub_u32_e32 v1, 0x10ff, v0
	v_writelane_b32 v242, s22, 53
	s_lshl_b32 s1, s36, 16
	v_and_b32_e32 v13, 0xc000, v13
	s_mov_b64 s[28:29], s[80:81]
	v_or_b32_e32 v10, 16, v6
	v_mov_b32_e32 v9, v87
	v_mul_u32_u24_e32 v11, 0x110, v2
	v_lshrrev_b32_e32 v2, 9, v1
	v_writelane_b32 v242, s23, 54
	v_or3_b32 v86, s1, v13, v8
	v_add_u32_e32 v12, 0, v126
	v_cmp_eq_u32_e64 s[4:5], 0, v6
	v_mul_u32_u24_e32 v132, 0x110, v6
	v_mul_u32_u24_e32 v16, 0x110, v10
	v_lshl_add_u64 v[92:93], s[38:39], 0, v[8:9]
	v_mul_u32_u24_e32 v9, 0x110, v84
	v_add_u32_e32 v1, 4, v2
	v_writelane_b32 v242, s28, 55
	v_readlane_b32 s88, v243, 49
	v_mov_b32_e32 v83, v87
	v_lshl_add_u64 v[94:95], s[28:29], 0, v[86:87]
	v_lshlrev_b32_e32 v86, 2, v6
	v_mbcnt_lo_u32_b32 v6, -1, 0
	v_add_u32_e32 v168, 4, v166
	v_add_u32_e32 v169, 0x50, v167
	v_add_u32_e32 v170, 8, v166
	v_add_u32_e32 v171, 0xa0, v167
	v_add_u32_e32 v175, 0xf0, v167
	v_add_u32_e32 v180, s24, v3
	v_add_u32_e32 v181, s25, v3
	v_add_u32_e32 v192, s24, v4
	v_add_u32_e32 v193, s25, v4
	v_and_b32_e32 v200, 28, v1
	v_mov_b32_e32 v1, v2
	v_mov_b32_e32 v4, v2
	v_mov_b32_e32 v3, v2
	v_writelane_b32 v242, s29, 56
	s_movk_i32 s33, 0x1000
	s_mov_b32 s26, 0x41000
	s_lshl_b32 s36, s0, 2
	v_add_u32_e32 v202, v7, v126
	s_mov_b32 s27, 0x5040100
	v_add_u32_e32 v203, v128, v16
	v_mbcnt_hi_u32_b32 v204, -1, v6
	s_add_i32 s28, 0, 0x185fc
	v_add_u32_e32 v205, v15, v9
	v_add_u32_e32 v206, v15, v11
	v_lshlrev_b32_e32 v96, 1, v10
	v_add_u32_e32 v207, v12, v132
	s_mov_b32 s61, s94
	s_mov_b32 s29, s94
	v_readlane_b32 s89, v243, 50
	v_readlane_b32 s90, v243, 51
	v_readlane_b32 s91, v243, 52
	v_writelane_b32 v242, s94, 57
	s_branch .LBB0_336

.LBB0_379:
	v_readlane_b32 s0, v242, 9
	v_readlane_b32 s8, v243, 49
	s_bitcmp0_b32 s0, 3
	v_readlane_b32 s9, v243, 50
	v_readlane_b32 s11, v243, 52
	v_readlane_b32 s10, v243, 51
	s_cbranch_scc1 .LBB0_448
	s_cmp_eq_u32 s98, 2
	s_cbranch_scc1 .LBB0_448
	s_add_u32 s2, s80, 0x36600000
	s_addc_u32 s3, s81, 0
	s_add_u32 s10, s80, 0x34200000
	s_addc_u32 s11, s81, 0
	s_add_u32 s8, s80, 0x400000
	s_addc_u32 s9, s81, 0
	s_lshl_b32 s0, s84, 5
	s_lshr_b32 s16, s85, 7
	s_and_b32 s17, s0, 32
	s_cmpk_lt_i32 s94, 0x400
	s_cselect_b64 s[0:1], -1, 0
	s_cmpk_gt_i32 s94, 0x3ff
	s_cbranch_scc1 .LBB0_392
	s_movk_i32 s4, 0xff
	s_and_b32 s12, s94, 7
	v_cmp_lt_u32_e32 vcc, s4, v0
	s_and_saveexec_b64 s[4:5], vcc
	s_xor_b64 s[4:5], exec, s[4:5]
	s_cbranch_execz .LBB0_387
	s_movk_i32 s6, 0x17f
	v_cmp_lt_u32_e32 vcc, s6, v0
	s_lshl_b32 s6, s12, 7
	v_add_u32_e32 v1, s6, v0
	s_and_saveexec_b64 s[6:7], vcc
	s_xor_b64 s[6:7], exec, s[6:7]
	v_add_u32_e32 v2, 0xa80, v1
	s_andn2_saveexec_b64 s[6:7], s[6:7]
	v_add_u32_e32 v2, 0x700, v1
	s_or_b64 exec, exec, s[6:7]

.LBB0_447:
	v_readlane_b32 s8, v243, 49
	v_readlane_b32 s9, v243, 50
	v_readlane_b32 s11, v243, 52
	s_barrier
	v_readlane_b32 s10, v243, 51
	s_cmp_eq_u32 s98, 1
	s_cbranch_scc0 .Lswap_done
	s_mov_b32 s98, 2
	s_branch .Lswap_prompt
.Lswap_done:
.LBB0_448:
	s_cmp_gt_i32 s9, 3
	v_readlane_b32 s2, v243, 55
	s_cselect_b64 s[0:1], -1, 0
	v_readlane_b32 s3, v243, 56
	s_and_b64 s[2:3], s[2:3], s[0:1]
	s_mov_b64 s[88:89], s[8:9]
	s_mov_b32 s91, s11
	s_andn2_b64 vcc, exec, s[2:3]
	s_cbranch_vccnz .LBB0_502
	s_waitcnt vmcnt(0)
	s_waitcnt vmcnt(0)
	s_barrier
	s_mov_b64 s[2:3], exec
	v_readlane_b32 s4, v243, 53
	v_readlane_b32 s5, v243, 54
	s_and_b64 s[4:5], s[2:3], s[4:5]
	s_mov_b64 exec, s[4:5]
	s_cbranch_execz .LBB0_501
	s_add_i32 s4, 0, 0x23f20
	v_mov_b32_e32 v1, s4
	s_waitcnt vmcnt(0) expcnt(0) lgkmcnt(0)
	ds_read_b32 v3, v1
	s_add_i32 s4, 0, 0x23f24
	v_mov_b32_e32 v1, s4
	ds_read_b32 v1, v1
	s_waitcnt lgkmcnt(1)
	v_cmp_ne_u32_e32 vcc, 0, v3
	s_cbranch_vccnz .LBB0_465
	s_load_dwordx2 s[8:9], s[92:93], 0x4
	s_add_u32 s4, s86, 0x1000
	s_addc_u32 s5, s87, 0
	s_add_u32 s6, s86, 0x1100
	s_addc_u32 s7, s87, 0
	v_readlane_b32 s10, v243, 0
	s_waitcnt lgkmcnt(0)
	s_mul_i32 s18, s8, s10
	s_add_u32 s8, s86, 0x1200
	s_mul_i32 s18, s18, s9
	s_addc_u32 s9, s87, 0
	s_add_u32 s10, s86, 0x1300
	s_addc_u32 s11, s87, 0
	s_mov_b32 s19, 1
	v_mov_b32_e32 v17, 0
	s_branch .LBB0_453

	.amdhsa_kernel _Z6mk_fwd4Args
		.amdhsa_group_segment_fixed_size 0
		.amdhsa_private_segment_fixed_size 0
		.amdhsa_kernarg_size 552
		.amdhsa_user_sgpr_count 2
		.amdhsa_user_sgpr_dispatch_ptr 0
		.amdhsa_user_sgpr_queue_ptr 0
		.amdhsa_user_sgpr_kernarg_segment_ptr 1
		.amdhsa_user_sgpr_dispatch_id 0
		.amdhsa_user_sgpr_kernarg_preload_length 0
		.amdhsa_user_sgpr_kernarg_preload_offset 0
		.amdhsa_user_sgpr_private_segment_size 0
		.amdhsa_uses_dynamic_stack 0
		.amdhsa_enable_private_segment 0
		.amdhsa_system_sgpr_workgroup_id_x 1
		.amdhsa_system_sgpr_workgroup_id_y 0
		.amdhsa_system_sgpr_workgroup_id_z 0
		.amdhsa_system_sgpr_workgroup_info 0
		.amdhsa_system_vgpr_workitem_id 0
		.amdhsa_next_free_vgpr 244
		.amdhsa_next_free_sgpr 102
		.amdhsa_accum_offset 244
		.amdhsa_reserve_vcc 1
		.amdhsa_float_round_mode_32 0
		.amdhsa_float_round_mode_16_64 0
		.amdhsa_float_denorm_mode_32 3
		.amdhsa_float_denorm_mode_16_64 3
		.amdhsa_dx10_clamp 1
		.amdhsa_ieee_mode 1
		.amdhsa_fp16_overflow 0
		.amdhsa_tg_split 0
		.amdhsa_exception_fp_ieee_invalid_op 0
		.amdhsa_exception_fp_denorm_src 0
		.amdhsa_exception_fp_ieee_div_zero 0
		.amdhsa_exception_fp_ieee_overflow 0
		.amdhsa_exception_fp_ieee_underflow 0
		.amdhsa_exception_fp_ieee_inexact 0
		.amdhsa_exception_int_div_zero 0
	.end_amdhsa_kernel

amdhsa.kernels:
  - .agpr_count:     0
    .args:
      - .offset:         0
        .size:           296
        .value_kind:     by_value
      - .offset:         296
        .size:           4
        .value_kind:     hidden_block_count_x
      - .offset:         300
        .size:           4
        .value_kind:     hidden_block_count_y
      - .offset:         304
        .size:           4
        .value_kind:     hidden_block_count_z
      - .offset:         308
        .size:           2
        .value_kind:     hidden_group_size_x
      - .offset:         310
        .size:           2
        .value_kind:     hidden_group_size_y
      - .offset:         312
        .size:           2
        .value_kind:     hidden_group_size_z
      - .offset:         314
        .size:           2
        .value_kind:     hidden_remainder_x
      - .offset:         316
        .size:           2
        .value_kind:     hidden_remainder_y
      - .offset:         318
        .size:           2
        .value_kind:     hidden_remainder_z
      - .offset:         336
        .size:           8
        .value_kind:     hidden_global_offset_x
      - .offset:         344
        .size:           8
        .value_kind:     hidden_global_offset_y
      - .offset:         352
        .size:           8
        .value_kind:     hidden_global_offset_z
      - .offset:         360
        .size:           2
        .value_kind:     hidden_grid_dims
      - .offset:         416
        .size:           4
        .value_kind:     hidden_dynamic_lds_size
    .group_segment_fixed_size: 0
    .kernarg_segment_align: 8
    .kernarg_segment_size: 552
    .language:       OpenCL C
    .language_version:
      - 2
      - 0
    .max_flat_workgroup_size: 512
    .name:           _Z6mk_fwd4Args
    .private_segment_fixed_size: 0
    .sgpr_count:     108
    .sgpr_spill_count: 124
    .symbol:         _Z6mk_fwd4Args.kd
    .uniform_work_group_size: 1
    .uses_dynamic_stack: false
    .vgpr_count:     244
    .vgpr_spill_count: 0
    .wavefront_size: 64
